# P6: sumsq prefetched at unit start and the epilogue's vmcnt(0) relaxed to vmcnt(8) so it no longer waits for the next unit's tile loads
# speedup vs baseline: 1.0032x; 1.0032x over previous
; __device__ __forceinline__ unsigned pk2(float lo, float hi) { return pg8::cvt_pk_bf16(lo, hi); }
; __device__ __forceinline__ float silu_f(float x) { return x * sigmoid_f(x); }
;     __device__ __forceinline__ void operator()(const f32x4 (&acc)[2][2][4][2], const pg8::Unit& u, int wr, int wc, int fr, int fq) const {
;         const int row0 = u.pm * 256 + wr * 64 + fr, col = u.pn * 128 + wc * 32 + 8 * fq;
; #pragma unroll
;         for (int ai = 0; ai < 2; ++ai)
; #pragma unroll
;             for (int m = 0; m < 4; ++m) {
;                 const int row = row0 + ai * 128 + m * 16;
;                 const float rs = sumsq ? rsqrtf(sumsq[row] * (1.f / 1024.f) + EPS) : 1.f;
;                 float o[8];
; #pragma unroll
;                 for (int n = 0; n < 2; ++n)
; #pragma unroll
;                     for (int e = 0; e < 4; ++e) { const float g = acc[ai][0][m][n][e] * rs, up = acc[ai][1][m][n][e] * rs; o[4 * n + e] = silu_f(g) * up; }
;                 u32x4 w; w.x = pk2(o[0], o[1]); w.y = pk2(o[2], o[3]); w.z = pk2(o[4], o[5]); w.w = pk2(o[6], o[7]);
;                 *(u32x4*)(H + (size_t)row * DFF + col) = w;
.LBB0_785:
	v_lshl_add_u32 v144, s0, 8, v148
	v_ashrrev_i32_e32 v145, 31, v144
	v_lshl_add_u64 v[146:147], v[144:145], 2, s[10:11]
	s_nop 0
	s_nop 0
	s_nop 0
	s_nop 0
	s_nop 0
	s_nop 0
	s_nop 0
	s_nop 0
	v_lshl_or_b32 v156, s1, 7, v150
	v_readlane_b32 s0, v235, 33
	v_mov_b32_e32 v161, v114
	v_mov_b32_e32 v114, v123
	v_readlane_b32 s1, v235, 34
	v_mov_b32_e32 v158, v124
	v_mov_b32_e32 v159, v116
	v_mov_b32_e32 v116, v125
	v_mov_b32_e32 v124, v126
	v_mov_b32_e32 v125, v118
	v_mov_b32_e32 v118, v127
	v_mov_b32_e32 v126, v120
	v_mov_b32_e32 v127, v112
	v_mov_b32_e32 v112, v121
	v_mov_b32_e32 v160, v122
	v_mov_b64_e32 v[120:121], s[0:1]
	v_ashrrev_i32_e32 v157, 31, v156
	v_or_b32_e32 v164, 16, v144
	v_mad_i64_i32 v[162:163], s[0:1], v144, s46, v[120:121]
	v_lshlrev_b64 v[122:123], 1, v[156:157]
	v_ashrrev_i32_e32 v165, 31, v164
	v_lshl_add_u64 v[156:157], v[162:163], 0, v[122:123]
	v_lshl_add_u64 v[162:163], v[164:165], 2, s[10:11]
	s_waitcnt vmcnt(8)
	v_mov_b32_e32 v145, v243
	v_fmamk_f32 v145, v145, 0x3a800000, v154
	v_mul_f32_e32 v155, 0x4b800000, v145
	v_cmp_gt_f32_e32 vcc, s45, v145
	s_nop 1
	v_cndmask_b32_e32 v145, v145, v155, vcc
	v_rsq_f32_e32 v145, v145
	s_nop 0
	v_mul_f32_e32 v155, 0x45800000, v145
	v_cndmask_b32_e32 v166, v145, v155, vcc
	v_pk_mul_f32 v[114:115], v[114:115], v[166:167] op_sel_hi:[1,0]
	v_pk_mul_f32 v[158:159], v[158:159], v[166:167] op_sel_hi:[1,0]
	v_pk_mul_f32 v[116:117], v[116:117], v[166:167] op_sel_hi:[1,0]
	v_pk_mul_f32 v[124:125], v[124:125], v[166:167] op_sel_hi:[1,0]
	v_pk_mul_f32 v[118:119], v[118:119], v[166:167] op_sel_hi:[1,0]
	v_pk_mul_f32 v[126:127], v[126:127], v[166:167] op_sel_hi:[1,0]
	v_pk_mul_f32 v[112:113], v[112:113], v[166:167] op_sel_hi:[1,0]
	v_pk_mul_f32 v[160:161], v[160:161], v[166:167] op_sel_hi:[1,0]
	v_mul_f32_e32 v170, 0xbfb8aa3b, v115
	v_mul_f32_e32 v145, 0xbfb8aa3b, v159
	v_mul_f32_e32 v155, 0xbfb8aa3b, v117
	v_mul_f32_e32 v165, 0xbfb8aa3b, v125
	v_mul_f32_e32 v166, 0xbfb8aa3b, v119
	v_mul_f32_e32 v167, 0xbfb8aa3b, v127
	v_mul_f32_e32 v168, 0xbfb8aa3b, v113
	v_mul_f32_e32 v169, 0xbfb8aa3b, v161
	v_exp_f32_e32 v170, v170
	v_exp_f32_e32 v145, v145
	v_exp_f32_e32 v155, v155
	v_exp_f32_e32 v165, v165
	v_exp_f32_e32 v166, v166
	v_exp_f32_e32 v167, v167
	v_exp_f32_e32 v168, v168
	v_exp_f32_e32 v169, v169
	v_add_f32_e32 v170, 1.0, v170
	v_add_f32_e32 v145, 1.0, v145
	v_add_f32_e32 v155, 1.0, v155
	v_add_f32_e32 v165, 1.0, v165
	v_add_f32_e32 v166, 1.0, v166
	v_add_f32_e32 v167, 1.0, v167
	v_add_f32_e32 v168, 1.0, v168
	v_add_f32_e32 v169, 1.0, v169
	v_rcp_f32_e32 v170, v170
	v_rcp_f32_e32 v145, v145
	v_rcp_f32_e32 v155, v155
	v_rcp_f32_e32 v165, v165
	v_rcp_f32_e32 v166, v166
	v_rcp_f32_e32 v167, v167
	v_rcp_f32_e32 v168, v168
	v_rcp_f32_e32 v169, v169
	v_mul_f32_e32 v115, v115, v170
	v_mul_f32_e32 v145, v159, v145
	v_mul_f32_e32 v117, v117, v155
	v_mul_f32_e32 v125, v125, v165
	v_mul_f32_e32 v119, v119, v166
	v_mul_f32_e32 v127, v127, v167
	v_mul_f32_e32 v113, v113, v168
	v_mul_f32_e32 v155, v161, v169
	v_mul_f32_e32 v115, v114, v115
	v_mul_f32_e32 v145, v158, v145
	v_mul_f32_e32 v116, v116, v117
	v_mul_f32_e32 v117, v124, v125
	v_mul_f32_e32 v118, v118, v119
	v_mul_f32_e32 v119, v126, v127
	v_mul_f32_e32 v124, v112, v113
	v_mul_f32_e32 v125, v160, v155
	v_cvt_pk_bf16_f32 v112, v145, v116
	v_cvt_pk_bf16_f32 v113, v117, v118
	v_cvt_pk_bf16_f32 v114, v119, v124
	v_cvt_pk_bf16_f32 v115, v125, v115
	global_store_dwordx4 v[156:157], v[112:115], off
	s_nop 0
	s_nop 0
	v_mov_b32_e32 v113, v100
	v_mov_b32_e32 v100, v109
	v_mov_b32_e32 v109, v102
	v_mov_b32_e32 v102, v111
	v_mov_b32_e32 v111, v96
	v_mov_b32_e32 v96, v105
	v_mov_b32_e32 v105, v98
	v_mov_b32_e32 v98, v107
	v_mov_b32_e32 v112, v108
	v_mov_b32_e32 v108, v110
	v_mov_b32_e32 v110, v104
	v_mov_b32_e32 v104, v106
	v_or_b32_e32 v106, 32, v144
	v_mad_i64_i32 v[114:115], s[0:1], v164, s46, v[120:121]
	v_lshl_add_u64 v[114:115], v[114:115], 0, v[122:123]
	s_nop 0
	v_fmamk_f32 v107, v236, 0x3a800000, v154
	v_mul_f32_e32 v116, 0x4b800000, v107
	v_cmp_gt_f32_e32 vcc, s45, v107
	s_nop 1
	v_cndmask_b32_e32 v107, v107, v116, vcc
	v_rsq_f32_e32 v118, v107
	v_ashrrev_i32_e32 v107, 31, v106
	v_lshl_add_u64 v[116:117], v[106:107], 2, s[10:11]
	v_mul_f32_e32 v107, 0x45800000, v118
	v_cndmask_b32_e32 v118, v118, v107, vcc
	v_pk_mul_f32 v[98:99], v[98:99], v[118:119] op_sel_hi:[1,0]
	v_pk_mul_f32 v[112:113], v[112:113], v[118:119] op_sel_hi:[1,0]
	v_pk_mul_f32 v[100:101], v[100:101], v[118:119] op_sel_hi:[1,0]
	v_pk_mul_f32 v[108:109], v[108:109], v[118:119] op_sel_hi:[1,0]
	v_pk_mul_f32 v[102:103], v[102:103], v[118:119] op_sel_hi:[1,0]
	v_pk_mul_f32 v[110:111], v[110:111], v[118:119] op_sel_hi:[1,0]
	v_pk_mul_f32 v[96:97], v[96:97], v[118:119] op_sel_hi:[1,0]
	v_pk_mul_f32 v[104:105], v[104:105], v[118:119] op_sel_hi:[1,0]
	v_mul_f32_e32 v145, 0xbfb8aa3b, v99
	v_mul_f32_e32 v107, 0xbfb8aa3b, v113
	v_mul_f32_e32 v118, 0xbfb8aa3b, v101
	v_mul_f32_e32 v119, 0xbfb8aa3b, v109
	v_mul_f32_e32 v124, 0xbfb8aa3b, v103
	v_mul_f32_e32 v125, 0xbfb8aa3b, v111
	v_mul_f32_e32 v126, 0xbfb8aa3b, v97
	v_mul_f32_e32 v127, 0xbfb8aa3b, v105
	v_exp_f32_e32 v145, v145
	v_exp_f32_e32 v107, v107
	v_exp_f32_e32 v118, v118
	v_exp_f32_e32 v119, v119
	v_exp_f32_e32 v124, v124
	v_exp_f32_e32 v125, v125
	v_exp_f32_e32 v126, v126
	v_exp_f32_e32 v127, v127
	v_add_f32_e32 v145, 1.0, v145
	v_add_f32_e32 v107, 1.0, v107
	v_add_f32_e32 v118, 1.0, v118
	v_add_f32_e32 v119, 1.0, v119
	v_add_f32_e32 v124, 1.0, v124
	v_add_f32_e32 v125, 1.0, v125
	v_add_f32_e32 v126, 1.0, v126
	v_add_f32_e32 v127, 1.0, v127
	v_rcp_f32_e32 v145, v145
	v_rcp_f32_e32 v107, v107
	v_rcp_f32_e32 v118, v118
; __device__ __forceinline__ unsigned pk2(float lo, float hi) { return pg8::cvt_pk_bf16(lo, hi); }
; __device__ __forceinline__ float silu_f(float x) { return x * sigmoid_f(x); }
;     __device__ __forceinline__ void operator()(const f32x4 (&acc)[2][2][4][2], const pg8::Unit& u, int wr, int wc, int fr, int fq) const {
;     ...
;                 const int row = row0 + ai * 128 + m * 16;
;                 const float rs = sumsq ? rsqrtf(sumsq[row] * (1.f / 1024.f) + EPS) : 1.f;
;                 float o[8];
; #pragma unroll
;                 for (int n = 0; n < 2; ++n)
; #pragma unroll
;                     for (int e = 0; e < 4; ++e) { const float g = acc[ai][0][m][n][e] * rs, up = acc[ai][1][m][n][e] * rs; o[4 * n + e] = silu_f(g) * up; }
;                 u32x4 w; w.x = pk2(o[0], o[1]); w.y = pk2(o[2], o[3]); w.z = pk2(o[4], o[5]); w.w = pk2(o[6], o[7]);
;                 *(u32x4*)(H + (size_t)row * DFF + col) = w;
	v_rcp_f32_e32 v119, v119
	v_rcp_f32_e32 v124, v124
	v_rcp_f32_e32 v125, v125
	v_rcp_f32_e32 v126, v126
	v_rcp_f32_e32 v127, v127
	v_mul_f32_e32 v99, v99, v145
	v_mul_f32_e32 v107, v113, v107
	v_mul_f32_e32 v101, v101, v118
	v_mul_f32_e32 v109, v109, v119
	v_mul_f32_e32 v103, v103, v124
	v_mul_f32_e32 v111, v111, v125
	v_mul_f32_e32 v97, v97, v126
	v_mul_f32_e32 v105, v105, v127
	v_mul_f32_e32 v99, v98, v99
	v_mul_f32_e32 v107, v112, v107
	v_mul_f32_e32 v100, v100, v101
	v_mul_f32_e32 v101, v108, v109
	v_mul_f32_e32 v102, v102, v103
	v_mul_f32_e32 v103, v110, v111
	v_mul_f32_e32 v108, v96, v97
	v_mul_f32_e32 v104, v104, v105
	v_cvt_pk_bf16_f32 v96, v107, v100
	v_cvt_pk_bf16_f32 v97, v101, v102
	v_cvt_pk_bf16_f32 v98, v103, v108
	v_cvt_pk_bf16_f32 v99, v104, v99
	global_store_dwordx4 v[114:115], v[96:99], off
	s_nop 0
	s_nop 0
	v_mov_b32_e32 v97, v84
	v_mov_b32_e32 v84, v93
	v_mov_b32_e32 v93, v86
	v_mov_b32_e32 v86, v95
	v_mov_b32_e32 v95, v80
	v_mov_b32_e32 v80, v89
	v_mov_b32_e32 v89, v82
	v_mov_b32_e32 v82, v91
	v_mov_b32_e32 v96, v92
	v_mov_b32_e32 v92, v94
	v_mov_b32_e32 v94, v88
	v_mov_b32_e32 v88, v90
	v_or_b32_e32 v90, 48, v144
	v_mad_i64_i32 v[98:99], s[0:1], v106, s46, v[120:121]
	v_lshl_add_u64 v[98:99], v[98:99], 0, v[122:123]
	s_nop 0
	v_fmamk_f32 v91, v237, 0x3a800000, v154
	v_mul_f32_e32 v100, 0x4b800000, v91
	v_cmp_gt_f32_e32 vcc, s45, v91
	s_nop 1
	v_cndmask_b32_e32 v91, v91, v100, vcc
	v_rsq_f32_e32 v102, v91
	v_ashrrev_i32_e32 v91, 31, v90
	v_lshl_add_u64 v[100:101], v[90:91], 2, s[10:11]
	v_mul_f32_e32 v91, 0x45800000, v102
	v_cndmask_b32_e32 v102, v102, v91, vcc
	v_pk_mul_f32 v[82:83], v[82:83], v[102:103] op_sel_hi:[1,0]
	v_pk_mul_f32 v[96:97], v[96:97], v[102:103] op_sel_hi:[1,0]
	v_pk_mul_f32 v[84:85], v[84:85], v[102:103] op_sel_hi:[1,0]
	v_pk_mul_f32 v[92:93], v[92:93], v[102:103] op_sel_hi:[1,0]
	v_pk_mul_f32 v[86:87], v[86:87], v[102:103] op_sel_hi:[1,0]
	v_pk_mul_f32 v[94:95], v[94:95], v[102:103] op_sel_hi:[1,0]
	v_pk_mul_f32 v[80:81], v[80:81], v[102:103] op_sel_hi:[1,0]
	v_pk_mul_f32 v[88:89], v[88:89], v[102:103] op_sel_hi:[1,0]
	v_mul_f32_e32 v108, 0xbfb8aa3b, v83
	v_mul_f32_e32 v91, 0xbfb8aa3b, v97
	v_mul_f32_e32 v102, 0xbfb8aa3b, v85
	v_mul_f32_e32 v103, 0xbfb8aa3b, v93
	v_mul_f32_e32 v104, 0xbfb8aa3b, v87
	v_mul_f32_e32 v105, 0xbfb8aa3b, v95
	v_mul_f32_e32 v106, 0xbfb8aa3b, v81
	v_mul_f32_e32 v107, 0xbfb8aa3b, v89
	v_exp_f32_e32 v108, v108
	v_exp_f32_e32 v91, v91
	v_exp_f32_e32 v102, v102
	v_exp_f32_e32 v103, v103
	v_exp_f32_e32 v104, v104
	v_exp_f32_e32 v105, v105
	v_exp_f32_e32 v106, v106
	v_exp_f32_e32 v107, v107
	v_add_f32_e32 v108, 1.0, v108
	v_add_f32_e32 v91, 1.0, v91
	v_add_f32_e32 v102, 1.0, v102
	v_add_f32_e32 v103, 1.0, v103
	v_add_f32_e32 v104, 1.0, v104
	v_add_f32_e32 v105, 1.0, v105
	v_add_f32_e32 v106, 1.0, v106
	v_add_f32_e32 v107, 1.0, v107
	v_rcp_f32_e32 v108, v108
	v_rcp_f32_e32 v91, v91
	v_rcp_f32_e32 v102, v102
	v_rcp_f32_e32 v103, v103
	v_rcp_f32_e32 v104, v104
	v_rcp_f32_e32 v105, v105
	v_rcp_f32_e32 v106, v106
	v_rcp_f32_e32 v107, v107
	v_mul_f32_e32 v83, v83, v108
	v_mul_f32_e32 v91, v97, v91
	v_mul_f32_e32 v85, v85, v102
	v_mul_f32_e32 v93, v93, v103
	v_mul_f32_e32 v87, v87, v104
	v_mul_f32_e32 v95, v95, v105
	v_mul_f32_e32 v81, v81, v106
	v_mul_f32_e32 v89, v89, v107
	v_mul_f32_e32 v83, v82, v83
	v_mul_f32_e32 v91, v96, v91
	v_mul_f32_e32 v84, v84, v85
	v_mul_f32_e32 v85, v92, v93
	v_mul_f32_e32 v86, v86, v87
	v_mul_f32_e32 v87, v94, v95
	v_mul_f32_e32 v92, v80, v81
	v_mul_f32_e32 v88, v88, v89
	v_cvt_pk_bf16_f32 v80, v91, v84
	v_cvt_pk_bf16_f32 v81, v85, v86
	v_cvt_pk_bf16_f32 v82, v87, v92
	v_cvt_pk_bf16_f32 v83, v88, v83
	global_store_dwordx4 v[98:99], v[80:83], off
	s_nop 0
	s_nop 0
	v_mov_b32_e32 v80, v76
	v_mov_b32_e32 v76, v78
	v_mov_b32_e32 v78, v68
	v_mov_b32_e32 v68, v70
	v_mov_b32_e32 v81, v72
	v_mov_b32_e32 v72, v77
	v_mov_b32_e32 v77, v74
	v_mov_b32_e32 v74, v79
	v_mov_b32_e32 v79, v64
	v_mov_b32_e32 v64, v69
	v_mov_b32_e32 v69, v66
	v_mov_b32_e32 v66, v71
	s_nop 0
	v_fmamk_f32 v70, v238, 0x3a800000, v154
	v_mul_f32_e32 v71, 0x4b800000, v70
	v_cmp_gt_f32_e32 vcc, s45, v70
	s_nop 1
	v_cndmask_b32_e32 v70, v70, v71, vcc
	v_rsq_f32_e32 v82, v70
	v_mad_i64_i32 v[70:71], s[0:1], v90, s46, v[120:121]
	v_lshl_add_u64 v[70:71], v[70:71], 0, v[122:123]
	v_mul_f32_e32 v83, 0x45800000, v82
	v_cndmask_b32_e32 v82, v82, v83, vcc
	v_pk_mul_f32 v[66:67], v[66:67], v[82:83] op_sel_hi:[1,0]
	v_pk_mul_f32 v[80:81], v[80:81], v[82:83] op_sel_hi:[1,0]
	v_pk_mul_f32 v[72:73], v[72:73], v[82:83] op_sel_hi:[1,0]
	v_pk_mul_f32 v[76:77], v[76:77], v[82:83] op_sel_hi:[1,0]
	v_pk_mul_f32 v[74:75], v[74:75], v[82:83] op_sel_hi:[1,0]
	v_pk_mul_f32 v[78:79], v[78:79], v[82:83] op_sel_hi:[1,0]
	v_pk_mul_f32 v[64:65], v[64:65], v[82:83] op_sel_hi:[1,0]
	v_pk_mul_f32 v[68:69], v[68:69], v[82:83] op_sel_hi:[1,0]
	v_mul_f32_e32 v89, 0xbfb8aa3b, v67
	v_mul_f32_e32 v82, 0xbfb8aa3b, v81
	v_mul_f32_e32 v83, 0xbfb8aa3b, v73
	v_mul_f32_e32 v84, 0xbfb8aa3b, v77
	v_mul_f32_e32 v85, 0xbfb8aa3b, v75
	v_mul_f32_e32 v86, 0xbfb8aa3b, v79
	v_mul_f32_e32 v87, 0xbfb8aa3b, v65
	v_mul_f32_e32 v88, 0xbfb8aa3b, v69
	v_exp_f32_e32 v89, v89
	v_exp_f32_e32 v82, v82
	v_exp_f32_e32 v83, v83
	v_exp_f32_e32 v84, v84
	v_exp_f32_e32 v85, v85
	v_exp_f32_e32 v86, v86
	v_exp_f32_e32 v87, v87
	v_exp_f32_e32 v88, v88
	v_add_f32_e32 v89, 1.0, v89
	v_add_f32_e32 v82, 1.0, v82
	v_add_f32_e32 v83, 1.0, v83
	v_add_f32_e32 v84, 1.0, v84
	v_add_f32_e32 v85, 1.0, v85
	v_add_f32_e32 v86, 1.0, v86
	v_add_f32_e32 v87, 1.0, v87
	v_add_f32_e32 v88, 1.0, v88
	v_rcp_f32_e32 v89, v89
	v_rcp_f32_e32 v82, v82
	v_rcp_f32_e32 v83, v83
; __device__ __forceinline__ unsigned pk2(float lo, float hi) { return pg8::cvt_pk_bf16(lo, hi); }
; __device__ __forceinline__ float silu_f(float x) { return x * sigmoid_f(x); }
;     __device__ __forceinline__ void operator()(const f32x4 (&acc)[2][2][4][2], const pg8::Unit& u, int wr, int wc, int fr, int fq) const {
;     ...
;                 const int row = row0 + ai * 128 + m * 16;
;                 const float rs = sumsq ? rsqrtf(sumsq[row] * (1.f / 1024.f) + EPS) : 1.f;
;                 float o[8];
; #pragma unroll
;                 for (int n = 0; n < 2; ++n)
; #pragma unroll
;                     for (int e = 0; e < 4; ++e) { const float g = acc[ai][0][m][n][e] * rs, up = acc[ai][1][m][n][e] * rs; o[4 * n + e] = silu_f(g) * up; }
;                 u32x4 w; w.x = pk2(o[0], o[1]); w.y = pk2(o[2], o[3]); w.z = pk2(o[4], o[5]); w.w = pk2(o[6], o[7]);
;                 *(u32x4*)(H + (size_t)row * DFF + col) = w;
	v_rcp_f32_e32 v84, v84
	v_rcp_f32_e32 v85, v85
	v_rcp_f32_e32 v86, v86
	v_rcp_f32_e32 v87, v87
	v_rcp_f32_e32 v88, v88
	v_mul_f32_e32 v67, v67, v89
	v_mul_f32_e32 v81, v81, v82
	v_mul_f32_e32 v73, v73, v83
	v_mul_f32_e32 v77, v77, v84
	v_mul_f32_e32 v75, v75, v85
	v_mul_f32_e32 v79, v79, v86
	v_mul_f32_e32 v65, v65, v87
	v_mul_f32_e32 v69, v69, v88
	v_mul_f32_e32 v67, v66, v67
	v_mul_f32_e32 v80, v80, v81
	v_mul_f32_e32 v72, v72, v73
	v_mul_f32_e32 v73, v76, v77
	v_mul_f32_e32 v74, v74, v75
	v_mul_f32_e32 v75, v78, v79
	v_mul_f32_e32 v76, v64, v65
	v_mul_f32_e32 v68, v68, v69
	v_cvt_pk_bf16_f32 v64, v80, v72
	v_cvt_pk_bf16_f32 v65, v73, v74
	v_cvt_pk_bf16_f32 v66, v75, v76
	v_cvt_pk_bf16_f32 v67, v68, v67
	global_store_dwordx4 v[70:71], v[64:67], off
	s_nop 0
	s_nop 0
	v_mov_b32_e32 v65, v56
	v_mov_b32_e32 v56, v61
	v_mov_b32_e32 v61, v58
	v_mov_b32_e32 v58, v63
	v_mov_b32_e32 v63, v48
	v_mov_b32_e32 v48, v53
	v_mov_b32_e32 v53, v50
	v_mov_b32_e32 v50, v55
	v_mov_b32_e32 v64, v60
	v_mov_b32_e32 v60, v62
	v_mov_b32_e32 v62, v52
	v_mov_b32_e32 v52, v54
	v_add_u32_e32 v54, 0x80, v144
	s_nop 0
	v_fmamk_f32 v55, v239, 0x3a800000, v154
	v_mul_f32_e32 v66, 0x4b800000, v55
	v_cmp_gt_f32_e32 vcc, s45, v55
	s_nop 1
	v_cndmask_b32_e32 v55, v55, v66, vcc
	v_rsq_f32_e32 v66, v55
	v_mad_i64_i32 v[54:55], s[0:1], v54, s46, v[120:121]
	v_lshl_add_u64 v[54:55], v[54:55], 0, v[122:123]
	v_mul_f32_e32 v67, 0x45800000, v66
	v_cndmask_b32_e32 v66, v66, v67, vcc
	v_pk_mul_f32 v[50:51], v[50:51], v[66:67] op_sel_hi:[1,0]
	v_pk_mul_f32 v[64:65], v[64:65], v[66:67] op_sel_hi:[1,0]
	v_pk_mul_f32 v[56:57], v[56:57], v[66:67] op_sel_hi:[1,0]
	v_pk_mul_f32 v[60:61], v[60:61], v[66:67] op_sel_hi:[1,0]
	v_pk_mul_f32 v[58:59], v[58:59], v[66:67] op_sel_hi:[1,0]
	v_pk_mul_f32 v[62:63], v[62:63], v[66:67] op_sel_hi:[1,0]
	v_pk_mul_f32 v[48:49], v[48:49], v[66:67] op_sel_hi:[1,0]
	v_pk_mul_f32 v[52:53], v[52:53], v[66:67] op_sel_hi:[1,0]
	v_mul_f32_e32 v73, 0xbfb8aa3b, v51
	v_mul_f32_e32 v66, 0xbfb8aa3b, v65
	v_mul_f32_e32 v67, 0xbfb8aa3b, v57
	v_mul_f32_e32 v68, 0xbfb8aa3b, v61
	v_mul_f32_e32 v69, 0xbfb8aa3b, v59
	v_mul_f32_e32 v70, 0xbfb8aa3b, v63
	v_mul_f32_e32 v71, 0xbfb8aa3b, v49
	v_mul_f32_e32 v72, 0xbfb8aa3b, v53
	v_exp_f32_e32 v73, v73
	v_exp_f32_e32 v66, v66
	v_exp_f32_e32 v67, v67
	v_exp_f32_e32 v68, v68
	v_exp_f32_e32 v69, v69
	v_exp_f32_e32 v70, v70
	v_exp_f32_e32 v71, v71
	v_exp_f32_e32 v72, v72
	v_add_f32_e32 v73, 1.0, v73
	v_add_f32_e32 v66, 1.0, v66
	v_add_f32_e32 v67, 1.0, v67
	v_add_f32_e32 v68, 1.0, v68
	v_add_f32_e32 v69, 1.0, v69
	v_add_f32_e32 v70, 1.0, v70
	v_add_f32_e32 v71, 1.0, v71
	v_add_f32_e32 v72, 1.0, v72
	v_rcp_f32_e32 v73, v73
	v_rcp_f32_e32 v66, v66
	v_rcp_f32_e32 v67, v67
	v_rcp_f32_e32 v68, v68
	v_rcp_f32_e32 v69, v69
	v_rcp_f32_e32 v70, v70
	v_rcp_f32_e32 v71, v71
	v_rcp_f32_e32 v72, v72
	v_mul_f32_e32 v51, v51, v73
	v_mul_f32_e32 v65, v65, v66
	v_mul_f32_e32 v57, v57, v67
	v_mul_f32_e32 v61, v61, v68
	v_mul_f32_e32 v59, v59, v69
	v_mul_f32_e32 v63, v63, v70
	v_mul_f32_e32 v49, v49, v71
	v_mul_f32_e32 v53, v53, v72
	v_mul_f32_e32 v51, v50, v51
	v_mul_f32_e32 v64, v64, v65
	v_mul_f32_e32 v56, v56, v57
	v_mul_f32_e32 v57, v60, v61
	v_mul_f32_e32 v58, v58, v59
	v_mul_f32_e32 v59, v62, v63
	v_mul_f32_e32 v60, v48, v49
	v_mul_f32_e32 v52, v52, v53
	v_cvt_pk_bf16_f32 v48, v64, v56
	v_cvt_pk_bf16_f32 v49, v57, v58
	v_cvt_pk_bf16_f32 v50, v59, v60
	v_cvt_pk_bf16_f32 v51, v52, v51
	global_store_dwordx4 v[54:55], v[48:51], off
	s_nop 0
	s_nop 0
	v_mov_b32_e32 v49, v40
	v_mov_b32_e32 v40, v45
	v_mov_b32_e32 v45, v42
	v_mov_b32_e32 v42, v47
	v_mov_b32_e32 v47, v32
	v_mov_b32_e32 v32, v37
	v_mov_b32_e32 v37, v34
	v_mov_b32_e32 v34, v39
	v_mov_b32_e32 v48, v44
	v_mov_b32_e32 v44, v46
	v_mov_b32_e32 v46, v36
	v_mov_b32_e32 v36, v38
	v_add_u32_e32 v38, 0x90, v144
	s_nop 0
	v_fmamk_f32 v39, v240, 0x3a800000, v154
	v_mul_f32_e32 v50, 0x4b800000, v39
	v_cmp_gt_f32_e32 vcc, s45, v39
	s_nop 1
	v_cndmask_b32_e32 v39, v39, v50, vcc
	v_rsq_f32_e32 v50, v39
	v_mad_i64_i32 v[38:39], s[0:1], v38, s46, v[120:121]
	v_lshl_add_u64 v[38:39], v[38:39], 0, v[122:123]
	v_mul_f32_e32 v51, 0x45800000, v50
	v_cndmask_b32_e32 v50, v50, v51, vcc
	v_pk_mul_f32 v[34:35], v[34:35], v[50:51] op_sel_hi:[1,0]
	v_pk_mul_f32 v[48:49], v[48:49], v[50:51] op_sel_hi:[1,0]
	v_pk_mul_f32 v[40:41], v[40:41], v[50:51] op_sel_hi:[1,0]
	v_pk_mul_f32 v[44:45], v[44:45], v[50:51] op_sel_hi:[1,0]
	v_pk_mul_f32 v[42:43], v[42:43], v[50:51] op_sel_hi:[1,0]
	v_pk_mul_f32 v[46:47], v[46:47], v[50:51] op_sel_hi:[1,0]
	v_pk_mul_f32 v[32:33], v[32:33], v[50:51] op_sel_hi:[1,0]
	v_pk_mul_f32 v[36:37], v[36:37], v[50:51] op_sel_hi:[1,0]
	v_mul_f32_e32 v57, 0xbfb8aa3b, v35
	v_mul_f32_e32 v50, 0xbfb8aa3b, v49
	v_mul_f32_e32 v51, 0xbfb8aa3b, v41
	v_mul_f32_e32 v52, 0xbfb8aa3b, v45
	v_mul_f32_e32 v53, 0xbfb8aa3b, v43
	v_mul_f32_e32 v54, 0xbfb8aa3b, v47
	v_mul_f32_e32 v55, 0xbfb8aa3b, v33
	v_mul_f32_e32 v56, 0xbfb8aa3b, v37
	v_exp_f32_e32 v57, v57
	v_exp_f32_e32 v50, v50
	v_exp_f32_e32 v51, v51
	v_exp_f32_e32 v52, v52
	v_exp_f32_e32 v53, v53
	v_exp_f32_e32 v54, v54
	v_exp_f32_e32 v55, v55
	v_exp_f32_e32 v56, v56
	v_add_f32_e32 v57, 1.0, v57
	v_add_f32_e32 v50, 1.0, v50
	v_add_f32_e32 v51, 1.0, v51
	v_add_f32_e32 v52, 1.0, v52
	v_add_f32_e32 v53, 1.0, v53
	v_add_f32_e32 v54, 1.0, v54
	v_add_f32_e32 v55, 1.0, v55
	v_add_f32_e32 v56, 1.0, v56
	v_rcp_f32_e32 v57, v57
	v_rcp_f32_e32 v50, v50
	v_rcp_f32_e32 v51, v51
	v_rcp_f32_e32 v52, v52
	v_rcp_f32_e32 v53, v53
	v_rcp_f32_e32 v54, v54
	v_rcp_f32_e32 v55, v55
	v_rcp_f32_e32 v56, v56
	v_mul_f32_e32 v35, v35, v57
	v_mul_f32_e32 v49, v49, v50
	v_mul_f32_e32 v41, v41, v51
; __device__ __forceinline__ unsigned pk2(float lo, float hi) { return pg8::cvt_pk_bf16(lo, hi); }
; __device__ __forceinline__ float silu_f(float x) { return x * sigmoid_f(x); }
; template <class Epi, class Sched, bool ALIGN_EPI = false, bool SP2 = false>
; __device__ __forceinline__ void gemm_phase(PG8_LAS unsigned char* lds, const Gemm g, const Sched& S, const Epi& E) {
;     ...
;         if (!has_next) break;
;     __device__ __forceinline__ void operator()(const f32x4 (&acc)[2][2][4][2], const pg8::Unit& u, int wr, int wc, int fr, int fq) const {
;     ...
;                 const int row = row0 + ai * 128 + m * 16;
;                 const float rs = sumsq ? rsqrtf(sumsq[row] * (1.f / 1024.f) + EPS) : 1.f;
;                 float o[8];
; #pragma unroll
;                 for (int n = 0; n < 2; ++n)
; #pragma unroll
;                     for (int e = 0; e < 4; ++e) { const float g = acc[ai][0][m][n][e] * rs, up = acc[ai][1][m][n][e] * rs; o[4 * n + e] = silu_f(g) * up; }
;                 u32x4 w; w.x = pk2(o[0], o[1]); w.y = pk2(o[2], o[3]); w.z = pk2(o[4], o[5]); w.w = pk2(o[6], o[7]);
;                 *(u32x4*)(H + (size_t)row * DFF + col) = w;
;             }
;     }
	v_mul_f32_e32 v45, v45, v52
	v_mul_f32_e32 v43, v43, v53
	v_mul_f32_e32 v47, v47, v54
	v_mul_f32_e32 v33, v33, v55
	v_mul_f32_e32 v37, v37, v56
	v_mul_f32_e32 v35, v34, v35
	v_mul_f32_e32 v48, v48, v49
	v_mul_f32_e32 v40, v40, v41
	v_mul_f32_e32 v41, v44, v45
	v_mul_f32_e32 v42, v42, v43
	v_mul_f32_e32 v43, v46, v47
	v_mul_f32_e32 v44, v32, v33
	v_mul_f32_e32 v36, v36, v37
	v_cvt_pk_bf16_f32 v32, v48, v40
	v_cvt_pk_bf16_f32 v33, v41, v42
	v_cvt_pk_bf16_f32 v34, v43, v44
	v_cvt_pk_bf16_f32 v35, v36, v35
	global_store_dwordx4 v[38:39], v[32:35], off
	s_nop 0
	s_nop 0
	v_mov_b32_e32 v33, v24
	v_mov_b32_e32 v24, v29
	v_mov_b32_e32 v29, v26
	v_mov_b32_e32 v26, v31
	v_mov_b32_e32 v31, v16
	v_mov_b32_e32 v16, v21
	v_mov_b32_e32 v21, v18
	v_mov_b32_e32 v18, v23
	v_mov_b32_e32 v32, v28
	v_mov_b32_e32 v28, v30
	v_mov_b32_e32 v30, v20
	v_mov_b32_e32 v20, v22
	v_add_u32_e32 v22, 0xa0, v144
	s_nop 0
	v_fmamk_f32 v23, v241, 0x3a800000, v154
	v_mul_f32_e32 v34, 0x4b800000, v23
	v_cmp_gt_f32_e32 vcc, s45, v23
	s_nop 1
	v_cndmask_b32_e32 v23, v23, v34, vcc
	v_rsq_f32_e32 v34, v23
	v_mad_i64_i32 v[22:23], s[0:1], v22, s46, v[120:121]
	v_lshl_add_u64 v[22:23], v[22:23], 0, v[122:123]
	v_mul_f32_e32 v35, 0x45800000, v34
	v_cndmask_b32_e32 v34, v34, v35, vcc
	v_pk_mul_f32 v[18:19], v[18:19], v[34:35] op_sel_hi:[1,0]
	v_pk_mul_f32 v[32:33], v[32:33], v[34:35] op_sel_hi:[1,0]
	v_pk_mul_f32 v[24:25], v[24:25], v[34:35] op_sel_hi:[1,0]
	v_pk_mul_f32 v[28:29], v[28:29], v[34:35] op_sel_hi:[1,0]
	v_pk_mul_f32 v[26:27], v[26:27], v[34:35] op_sel_hi:[1,0]
	v_pk_mul_f32 v[30:31], v[30:31], v[34:35] op_sel_hi:[1,0]
	v_pk_mul_f32 v[16:17], v[16:17], v[34:35] op_sel_hi:[1,0]
	v_pk_mul_f32 v[20:21], v[20:21], v[34:35] op_sel_hi:[1,0]
	v_mul_f32_e32 v41, 0xbfb8aa3b, v19
	v_mul_f32_e32 v34, 0xbfb8aa3b, v33
	v_mul_f32_e32 v35, 0xbfb8aa3b, v25
	v_mul_f32_e32 v36, 0xbfb8aa3b, v29
	v_mul_f32_e32 v37, 0xbfb8aa3b, v27
	v_mul_f32_e32 v38, 0xbfb8aa3b, v31
	v_mul_f32_e32 v39, 0xbfb8aa3b, v17
	v_mul_f32_e32 v40, 0xbfb8aa3b, v21
	v_exp_f32_e32 v41, v41
	v_exp_f32_e32 v34, v34
	v_exp_f32_e32 v35, v35
	v_exp_f32_e32 v36, v36
	v_exp_f32_e32 v37, v37
	v_exp_f32_e32 v38, v38
	v_exp_f32_e32 v39, v39
	v_exp_f32_e32 v40, v40
	v_add_f32_e32 v41, 1.0, v41
	v_add_f32_e32 v34, 1.0, v34
	v_add_f32_e32 v35, 1.0, v35
	v_add_f32_e32 v36, 1.0, v36
	v_add_f32_e32 v37, 1.0, v37
	v_add_f32_e32 v38, 1.0, v38
	v_add_f32_e32 v39, 1.0, v39
	v_add_f32_e32 v40, 1.0, v40
	v_rcp_f32_e32 v41, v41
	v_rcp_f32_e32 v34, v34
	v_rcp_f32_e32 v35, v35
	v_rcp_f32_e32 v36, v36
	v_rcp_f32_e32 v37, v37
	v_rcp_f32_e32 v38, v38
	v_rcp_f32_e32 v39, v39
	v_rcp_f32_e32 v40, v40
	v_mul_f32_e32 v19, v19, v41
	v_mul_f32_e32 v33, v33, v34
	v_mul_f32_e32 v25, v25, v35
	v_mul_f32_e32 v29, v29, v36
	v_mul_f32_e32 v27, v27, v37
	v_mul_f32_e32 v31, v31, v38
	v_mul_f32_e32 v17, v17, v39
	v_mul_f32_e32 v21, v21, v40
	v_mul_f32_e32 v19, v18, v19
	v_mul_f32_e32 v32, v32, v33
	v_mul_f32_e32 v24, v24, v25
	v_mul_f32_e32 v25, v28, v29
	v_mul_f32_e32 v26, v26, v27
	v_mul_f32_e32 v27, v30, v31
	v_mul_f32_e32 v28, v16, v17
	v_mul_f32_e32 v20, v20, v21
	v_cvt_pk_bf16_f32 v16, v32, v24
	v_cvt_pk_bf16_f32 v17, v25, v26
	v_cvt_pk_bf16_f32 v18, v27, v28
	v_cvt_pk_bf16_f32 v19, v20, v19
	global_store_dwordx4 v[22:23], v[16:19], off
	s_nop 0
	s_andn2_b64 vcc, exec, s[4:5]
	v_mov_b32_e32 v17, v8
	v_mov_b32_e32 v8, v13
	v_mov_b32_e32 v13, v10
	v_mov_b32_e32 v10, v15
	v_mov_b32_e32 v15, v0
	v_mov_b32_e32 v0, v5
	v_mov_b32_e32 v5, v2
	v_mov_b32_e32 v2, v7
	v_mov_b32_e32 v16, v12
	v_mov_b32_e32 v12, v14
	v_mov_b32_e32 v14, v4
	v_mov_b32_e32 v4, v6
	v_add_u32_e32 v6, 0xb0, v144
	s_nop 0
	v_fmamk_f32 v7, v242, 0x3a800000, v154
	v_mul_f32_e32 v18, 0x4b800000, v7
	v_cmp_gt_f32_e64 s[0:1], s45, v7
	s_nop 1
	v_cndmask_b32_e64 v7, v7, v18, s[0:1]
	v_rsq_f32_e32 v18, v7
	v_mad_i64_i32 v[6:7], s[22:23], v6, s46, v[120:121]
	v_lshl_add_u64 v[6:7], v[6:7], 0, v[122:123]
	v_mul_f32_e32 v19, 0x45800000, v18
	v_cndmask_b32_e64 v18, v18, v19, s[0:1]
	v_pk_mul_f32 v[2:3], v[2:3], v[18:19] op_sel_hi:[1,0]
	v_pk_mul_f32 v[16:17], v[16:17], v[18:19] op_sel_hi:[1,0]
	v_pk_mul_f32 v[8:9], v[8:9], v[18:19] op_sel_hi:[1,0]
	v_pk_mul_f32 v[12:13], v[12:13], v[18:19] op_sel_hi:[1,0]
	v_pk_mul_f32 v[10:11], v[10:11], v[18:19] op_sel_hi:[1,0]
	v_pk_mul_f32 v[14:15], v[14:15], v[18:19] op_sel_hi:[1,0]
	v_pk_mul_f32 v[0:1], v[0:1], v[18:19] op_sel_hi:[1,0]
	v_pk_mul_f32 v[4:5], v[4:5], v[18:19] op_sel_hi:[1,0]
	v_mul_f32_e32 v25, 0xbfb8aa3b, v3
	v_mul_f32_e32 v18, 0xbfb8aa3b, v17
	v_mul_f32_e32 v19, 0xbfb8aa3b, v9
	v_mul_f32_e32 v20, 0xbfb8aa3b, v13
	v_mul_f32_e32 v21, 0xbfb8aa3b, v11
	v_mul_f32_e32 v22, 0xbfb8aa3b, v15
	v_mul_f32_e32 v23, 0xbfb8aa3b, v1
	v_mul_f32_e32 v24, 0xbfb8aa3b, v5
	v_exp_f32_e32 v25, v25
	v_exp_f32_e32 v18, v18
	v_exp_f32_e32 v19, v19
	v_exp_f32_e32 v20, v20
	v_exp_f32_e32 v21, v21
	v_exp_f32_e32 v22, v22
	v_exp_f32_e32 v23, v23
	v_exp_f32_e32 v24, v24
	v_add_f32_e32 v25, 1.0, v25
	v_add_f32_e32 v18, 1.0, v18
	v_add_f32_e32 v19, 1.0, v19
	v_add_f32_e32 v20, 1.0, v20
	v_add_f32_e32 v21, 1.0, v21
	v_add_f32_e32 v22, 1.0, v22
	v_add_f32_e32 v23, 1.0, v23
	v_add_f32_e32 v24, 1.0, v24
	v_rcp_f32_e32 v25, v25
	v_rcp_f32_e32 v18, v18
	v_rcp_f32_e32 v19, v19
	v_rcp_f32_e32 v20, v20
	v_rcp_f32_e32 v21, v21
	v_rcp_f32_e32 v22, v22
	v_rcp_f32_e32 v23, v23
	v_rcp_f32_e32 v24, v24
	v_mul_f32_e32 v3, v3, v25
	v_mul_f32_e32 v17, v17, v18
	v_mul_f32_e32 v9, v9, v19
	v_mul_f32_e32 v13, v13, v20
	v_mul_f32_e32 v11, v11, v21
	v_mul_f32_e32 v15, v15, v22
	v_mul_f32_e32 v1, v1, v23
	v_mul_f32_e32 v5, v5, v24
	v_mul_f32_e32 v3, v2, v3
	s_mov_b64 s[0:1], -1
	v_mul_f32_e32 v16, v16, v17
	v_mul_f32_e32 v8, v8, v9
	v_mul_f32_e32 v9, v12, v13
	v_mul_f32_e32 v10, v10, v11
	v_mul_f32_e32 v11, v14, v15
	v_mul_f32_e32 v12, v0, v1
	v_mul_f32_e32 v4, v4, v5
	v_cvt_pk_bf16_f32 v0, v16, v8
	v_cvt_pk_bf16_f32 v1, v9, v10
	v_cvt_pk_bf16_f32 v2, v11, v12
	v_cvt_pk_bf16_f32 v3, v4, v3
	global_store_dwordx4 v[6:7], v[0:3], off
	s_cbranch_vccnz .LBB0_778
	s_andn2_b64 vcc, exec, s[2:3]
	s_cbranch_vccnz .LBB0_777
	s_barrier
	s_branch .LBB0_777
